# FF2 layer-0 leftover round: split-K x4 over 4 workgroups, partial sums added into the residual in a fixed order (turn counter, release/acquire), no float atomics
# baseline (speedup 1.0000x reference)
;     __host__ __device__ bool next(int i, Unit& u) const {
;         const long L = (long)i * G + c; if (L >= nwg) return false;
;         int wgid = (int)L; { const int q = nwg / NXCD, r = nwg % NXCD, xcd = wgid % NXCD, off = wgid / NXCD; wgid = (xcd < r ? xcd * (q + 1) : r * (q + 1) + (xcd - r) * q) + off; }
;         const int nig = wgm * nN, gid = wgid / nig, fm = gid * wgm, gsz = (nM - fm) < wgm ? (nM - fm) : wgm;
;         u.pm = fm + ((wgid % nig) % gsz); u.pn = (wgid % nig) / gsz; return true;
; template <class Epi, class Sched>
; __device__ __forceinline__ void gemm_phase(LAS unsigned char* lds, const Gemm g, const Sched& S, const Epi& E) {
;     ...
;     const char* cA = (const char*)g.A + (size_t)cur.pm * tstep; const char* cB = (const char*)g.Bt + (size_t)cur.pn * tstep;
.Lsk_not3:
	s_cmp_lg_u32 s36, 2
	s_cbranch_scc1 .Lsk_hdr_done
	s_lshr_b32 s8, s54, 2
	s_addk_i32 s8, 0x200
	s_mov_b32 s9, 0
	s_and_b32 s22, s54, 3
	s_lshl_b32 s22, s22, 12

; #define PG8_STAGE(bufoff, gbase, voff) do { _Pragma("unroll") for (int _i = 0; _i < 2; ++_i) \
;         __builtin_amdgcn_global_load_lds((const unsigned*)((const char*)(gbase) + (voff)[_i]), (LAS unsigned*)(lds + (bufoff) + ldsw + _i * 8192), 16, 0, 0); } while (0)
; #define PG8_LDA(dst, b, h) do { _Pragma("unroll") for (int m = 0; m < 4; ++m) _Pragma("unroll") for (int k = 0; k < 2; ++k) dst[m][k] = *(const LAS bf16x8*)(lds + PG8_SA(b, h) + aoff + m * 2048 + k * 1024); } while (0)
; #define PG8_LDB(dst, b, h) do { _Pragma("unroll") for (int n = 0; n < 2; ++n) _Pragma("unroll") for (int k = 0; k < 2; ++k) dst[n][k] = *(const LAS bf16x8*)(lds + PG8_SB(b, h) + boff + n * 2048 + k * 1024); } while (0)
; #define PG8_MMA(ai, bj, At, Bt) do { __builtin_amdgcn_s_setprio(1); _Pragma("unroll") for (int m = 0; m < 4; ++m) _Pragma("unroll") for (int n = 0; n < 2; ++n) _Pragma("unroll") for (int k = 0; k < 2; ++k) \
;         acc[ai][bj][m][n] = __builtin_amdgcn_mfma_f32_16x16x32_bf16(Bt[n][k], At[m][k], acc[ai][bj][m][n], 0, 0, 0); __builtin_amdgcn_s_setprio(0); } while (0)
; #define PG8_WAIT_V(n) asm volatile("s_waitcnt vmcnt(" #n ")" ::: "memory")
; #define PG8_WAIT_L(n) asm volatile("s_waitcnt lgkmcnt(" #n ")" ::: "memory")
; #define PG8_BAR __builtin_amdgcn_s_barrier()
; #define PG8_SCHED __builtin_amdgcn_sched_barrier(0)
; template <class Epi, class Sched>
; __device__ __forceinline__ void gemm_phase(LAS unsigned char* lds, const Gemm g, const Sched& S, const Epi& E) {
;     ...
;             PG8_LDB(B0, 0, 0); PG8_SCHED; PG8_LDA(At, 0, 0); PG8_STAGE(PG8_SA(1, 1), a1 + hstep, voffA);
;             PG8_WAIT_L(8); PG8_BAR; PG8_WAIT_L(0); PG8_MMA(0, 0, At, B0); PG8_BAR; PG8_SCHED;
;             PG8_LDB(B1, 0, 1); PG8_STAGE(PG8_SB(0, 0), b2, voffB);
;             PG8_BAR; PG8_WAIT_L(0); PG8_MMA(0, 1, At, B1); PG8_BAR;
;             PG8_LDA(At, 0, 1); PG8_STAGE(PG8_SA(0, 0), a2, voffA);
;             PG8_BAR; PG8_WAIT_L(0); PG8_MMA(1, 0, At, B0); PG8_BAR; PG8_SCHED;
;             PG8_STAGE(PG8_SB(0, 1), b2 + hstep, voffB);
;             PG8_WAIT_V(6); PG8_BAR; PG8_MMA(1, 1, At, B1); PG8_BAR;
.LBB0_1343:
	s_nop 0
	v_add_u32_e32 v136, s42, v139
	ds_read_b128 v[142:145], v136
	ds_read_b128 v[146:149], v136 offset:1024
	ds_read_b128 v[150:153], v136 offset:2048
	ds_read_b128 v[154:157], v136 offset:3072
	s_add_u32 s18, s16, 0x100
	s_addc_u32 s19, s17, 0
	s_cmpk_eq_i32 s40, 0x7c
	s_cselect_b32 s23, s3, s19
	s_cselect_b32 s22, s7, s18
	s_cselect_b32 s21, s5, s39
	s_cselect_b32 s20, s37, s38
	v_lshl_add_u64 v[136:137], s[16:17], 0, v[132:133]
	s_add_i32 m0, s13, 0xc000
	ds_read_b128 v[158:161], v141
	ds_read_b128 v[162:165], v141 offset:1024
	ds_read_b128 v[166:169], v141 offset:2048
	ds_read_b128 v[170:173], v141 offset:3072
	ds_read_b128 v[174:177], v141 offset:4096
	ds_read_b128 v[178:181], v141 offset:5120
	ds_read_b128 v[182:185], v141 offset:6144
	ds_read_b128 v[186:189], v141 offset:7168
	global_load_lds_dwordx4 v[136:137], off
	v_lshl_add_u64 v[136:137], s[16:17], 0, v[134:135]
	s_add_i32 m0, s13, 0xe000
	s_nop 0
	global_load_lds_dwordx4 v[136:137], off
	s_waitcnt lgkmcnt(8)
	s_barrier
	s_waitcnt lgkmcnt(0)
	s_setprio 1
	s_waitcnt lgkmcnt(0)
	v_mfma_f32_16x16x32_bf16 v[126:129], v[142:145], v[158:161], v[126:129]
	v_mfma_f32_16x16x32_bf16 v[122:125], v[150:153], v[158:161], v[122:125]
	v_mfma_f32_16x16x32_bf16 v[110:113], v[142:145], v[166:169], v[110:113]
	v_mfma_f32_16x16x32_bf16 v[106:109], v[150:153], v[166:169], v[106:109]
	v_mfma_f32_16x16x32_bf16 v[94:97], v[142:145], v[174:177], v[94:97]
	v_mfma_f32_16x16x32_bf16 v[90:93], v[150:153], v[174:177], v[90:93]
	v_mfma_f32_16x16x32_bf16 v[78:81], v[142:145], v[182:185], v[78:81]
	v_mfma_f32_16x16x32_bf16 v[74:77], v[150:153], v[182:185], v[74:77]
	v_mfma_f32_16x16x32_bf16 v[126:129], v[146:149], v[162:165], v[126:129]
	v_mfma_f32_16x16x32_bf16 v[122:125], v[154:157], v[162:165], v[122:125]
	v_mfma_f32_16x16x32_bf16 v[110:113], v[146:149], v[170:173], v[110:113]
	v_mfma_f32_16x16x32_bf16 v[106:109], v[154:157], v[170:173], v[106:109]
	v_mfma_f32_16x16x32_bf16 v[94:97], v[146:149], v[178:181], v[94:97]
	v_mfma_f32_16x16x32_bf16 v[90:93], v[154:157], v[178:181], v[90:93]
	v_mfma_f32_16x16x32_bf16 v[78:81], v[146:149], v[186:189], v[78:81]
	v_mfma_f32_16x16x32_bf16 v[74:77], v[154:157], v[186:189], v[74:77]
	s_setprio 0
	s_barrier
	s_add_i32 s41, 0, 0x14000
	v_add_u32_e32 v136, s41, v139
	s_add_i32 s16, s42, s28
	ds_read_b128 v[190:193], v136
	ds_read_b128 v[194:197], v136 offset:1024
	ds_read_b128 v[198:201], v136 offset:2048
	ds_read_b128 v[202:205], v136 offset:3072
	v_lshl_add_u64 v[136:137], s[20:21], 0, v[0:1]
	s_mov_b32 m0, s16
	v_lshl_add_u64 v[206:207], s[20:21], 0, v[130:131]
	global_load_lds_dwordx4 v[136:137], off
	s_add_i32 m0, s16, 0x2000
	s_nop 0
	global_load_lds_dwordx4 v[206:207], off
	s_barrier
	s_waitcnt lgkmcnt(0)
	s_setprio 1
	s_waitcnt lgkmcnt(0)
	v_mfma_f32_16x16x32_bf16 v[118:121], v[190:193], v[158:161], v[118:121]
	v_mfma_f32_16x16x32_bf16 v[114:117], v[198:201], v[158:161], v[114:117]
	v_mfma_f32_16x16x32_bf16 v[102:105], v[190:193], v[166:169], v[102:105]
	v_mfma_f32_16x16x32_bf16 v[98:101], v[198:201], v[166:169], v[98:101]
	v_mfma_f32_16x16x32_bf16 v[86:89], v[190:193], v[174:177], v[86:89]
	v_mfma_f32_16x16x32_bf16 v[82:85], v[198:201], v[174:177], v[82:85]
	v_mfma_f32_16x16x32_bf16 v[70:73], v[190:193], v[182:185], v[70:73]
	v_mfma_f32_16x16x32_bf16 v[66:69], v[198:201], v[182:185], v[66:69]
	v_mfma_f32_16x16x32_bf16 v[118:121], v[194:197], v[162:165], v[118:121]
	v_mfma_f32_16x16x32_bf16 v[114:117], v[202:205], v[162:165], v[114:117]
	v_mfma_f32_16x16x32_bf16 v[102:105], v[194:197], v[170:173], v[102:105]
	v_mfma_f32_16x16x32_bf16 v[98:101], v[202:205], v[170:173], v[98:101]
	v_mfma_f32_16x16x32_bf16 v[86:89], v[194:197], v[178:181], v[86:89]
	v_mfma_f32_16x16x32_bf16 v[82:85], v[202:205], v[178:181], v[82:85]
	v_mfma_f32_16x16x32_bf16 v[70:73], v[194:197], v[186:189], v[70:73]
	v_mfma_f32_16x16x32_bf16 v[66:69], v[202:205], v[186:189], v[66:69]
	s_setprio 0
	s_mov_b32 m0, s13
	v_lshl_add_u64 v[208:209], s[22:23], 0, v[0:1]
	s_barrier
	ds_read_b128 v[158:161], v141 offset:16384
	ds_read_b128 v[162:165], v141 offset:17408
	ds_read_b128 v[166:169], v141 offset:18432
	ds_read_b128 v[170:173], v141 offset:19456
	ds_read_b128 v[174:177], v141 offset:20480
	ds_read_b128 v[178:181], v141 offset:21504
	ds_read_b128 v[182:185], v141 offset:22528
	ds_read_b128 v[186:189], v141 offset:23552
	global_load_lds_dwordx4 v[208:209], off
	v_lshl_add_u64 v[210:211], s[22:23], 0, v[130:131]
	s_mov_b32 m0, s15
	s_nop 0
	global_load_lds_dwordx4 v[210:211], off
	s_barrier
	s_waitcnt lgkmcnt(0)
	s_setprio 1
	s_waitcnt lgkmcnt(0)
	v_mfma_f32_16x16x32_bf16 v[62:65], v[142:145], v[158:161], v[62:65]
	v_mfma_f32_16x16x32_bf16 v[58:61], v[150:153], v[158:161], v[58:61]
	v_mfma_f32_16x16x32_bf16 v[46:49], v[142:145], v[166:169], v[46:49]
	v_mfma_f32_16x16x32_bf16 v[42:45], v[150:153], v[166:169], v[42:45]
	v_mfma_f32_16x16x32_bf16 v[30:33], v[142:145], v[174:177], v[30:33]
	v_mfma_f32_16x16x32_bf16 v[26:29], v[150:153], v[174:177], v[26:29]
	v_mfma_f32_16x16x32_bf16 v[14:17], v[142:145], v[182:185], v[14:17]
	v_mfma_f32_16x16x32_bf16 v[10:13], v[150:153], v[182:185], v[10:13]
	v_mfma_f32_16x16x32_bf16 v[62:65], v[146:149], v[162:165], v[62:65]
	v_mfma_f32_16x16x32_bf16 v[58:61], v[154:157], v[162:165], v[58:61]
	v_mfma_f32_16x16x32_bf16 v[46:49], v[146:149], v[170:173], v[46:49]
	v_mfma_f32_16x16x32_bf16 v[42:45], v[154:157], v[170:173], v[42:45]
	v_mfma_f32_16x16x32_bf16 v[30:33], v[146:149], v[178:181], v[30:33]
	v_mfma_f32_16x16x32_bf16 v[26:29], v[154:157], v[178:181], v[26:29]
	v_mfma_f32_16x16x32_bf16 v[14:17], v[146:149], v[186:189], v[14:17]
	v_mfma_f32_16x16x32_bf16 v[10:13], v[154:157], v[186:189], v[10:13]
	s_setprio 0
	s_barrier
; #define PG8_STAGE(bufoff, gbase, voff) do { _Pragma("unroll") for (int _i = 0; _i < 2; ++_i) \
;         __builtin_amdgcn_global_load_lds((const unsigned*)((const char*)(gbase) + (voff)[_i]), (LAS unsigned*)(lds + (bufoff) + ldsw + _i * 8192), 16, 0, 0); } while (0)
; #define PG8_LDA(dst, b, h) do { _Pragma("unroll") for (int m = 0; m < 4; ++m) _Pragma("unroll") for (int k = 0; k < 2; ++k) dst[m][k] = *(const LAS bf16x8*)(lds + PG8_SA(b, h) + aoff + m * 2048 + k * 1024); } while (0)
; #define PG8_LDB(dst, b, h) do { _Pragma("unroll") for (int n = 0; n < 2; ++n) _Pragma("unroll") for (int k = 0; k < 2; ++k) dst[n][k] = *(const LAS bf16x8*)(lds + PG8_SB(b, h) + boff + n * 2048 + k * 1024); } while (0)
; #define PG8_MMA(ai, bj, At, Bt) do { __builtin_amdgcn_s_setprio(1); _Pragma("unroll") for (int m = 0; m < 4; ++m) _Pragma("unroll") for (int n = 0; n < 2; ++n) _Pragma("unroll") for (int k = 0; k < 2; ++k) \
;         acc[ai][bj][m][n] = __builtin_amdgcn_mfma_f32_16x16x32_bf16(Bt[n][k], At[m][k], acc[ai][bj][m][n], 0, 0, 0); __builtin_amdgcn_s_setprio(0); } while (0)
; #define PG8_WAIT_V(n) asm volatile("s_waitcnt vmcnt(" #n ")" ::: "memory")
; #define PG8_WAIT_L(n) asm volatile("s_waitcnt lgkmcnt(" #n ")" ::: "memory")
; #define PG8_BAR __builtin_amdgcn_s_barrier()
; #define PG8_SCHED __builtin_amdgcn_sched_barrier(0)
; template <class Epi, class Sched>
; __device__ __forceinline__ void gemm_phase(LAS unsigned char* lds, const Gemm g, const Sched& S, const Epi& E) {
;     ...
;             PG8_BAR; PG8_WAIT_L(0); PG8_MMA(1, 0, At, B0); PG8_BAR; PG8_SCHED;
;             PG8_STAGE(PG8_SB(0, 1), b2 + hstep, voffB);
;             PG8_WAIT_V(6); PG8_BAR; PG8_MMA(1, 1, At, B1); PG8_BAR;
;             PG8_LDB(B0, 1, 0); PG8_SCHED; PG8_LDA(At, 1, 0); PG8_STAGE(PG8_SA(0, 1), a2 + hstep, voffA);
;             PG8_WAIT_L(8); PG8_BAR; PG8_WAIT_L(0); PG8_MMA(0, 0, At, B0); PG8_BAR; PG8_SCHED;
;             PG8_LDB(B1, 1, 1); PG8_STAGE(PG8_SB(1, 0), b3, voffB);
;             PG8_BAR; PG8_WAIT_L(0); PG8_MMA(0, 1, At, B1); PG8_BAR;
	s_add_u32 s16, s20, 0x200000
	s_addc_u32 s17, s21, 0
	s_add_i32 s41, s41, s28
	v_lshl_add_u64 v[142:143], s[16:17], 0, v[0:1]
	s_mov_b32 m0, s41
	s_nop 0
	global_load_lds_dwordx4 v[142:143], off
	v_lshl_add_u64 v[142:143], s[16:17], 0, v[130:131]
	s_add_i32 m0, s41, 0x2000
	s_nop 0
	global_load_lds_dwordx4 v[142:143], off
	s_waitcnt vmcnt(6)
	s_barrier
	s_setprio 1
	v_mfma_f32_16x16x32_bf16 v[54:57], v[190:193], v[158:161], v[54:57]
	v_mfma_f32_16x16x32_bf16 v[50:53], v[198:201], v[158:161], v[50:53]
	v_mfma_f32_16x16x32_bf16 v[38:41], v[190:193], v[166:169], v[38:41]
	v_mfma_f32_16x16x32_bf16 v[34:37], v[198:201], v[166:169], v[34:37]
	v_mfma_f32_16x16x32_bf16 v[22:25], v[190:193], v[174:177], v[22:25]
	v_mfma_f32_16x16x32_bf16 v[18:21], v[198:201], v[174:177], v[18:21]
	v_mfma_f32_16x16x32_bf16 v[6:9], v[190:193], v[182:185], v[6:9]
	v_mfma_f32_16x16x32_bf16 v[2:5], v[198:201], v[182:185], v[2:5]
	v_mfma_f32_16x16x32_bf16 v[54:57], v[194:197], v[162:165], v[54:57]
	v_mfma_f32_16x16x32_bf16 v[50:53], v[202:205], v[162:165], v[50:53]
	v_mfma_f32_16x16x32_bf16 v[38:41], v[194:197], v[170:173], v[38:41]
	v_mfma_f32_16x16x32_bf16 v[34:37], v[202:205], v[170:173], v[34:37]
	v_mfma_f32_16x16x32_bf16 v[22:25], v[194:197], v[178:181], v[22:25]
	v_mfma_f32_16x16x32_bf16 v[18:21], v[202:205], v[178:181], v[18:21]
	v_mfma_f32_16x16x32_bf16 v[6:9], v[194:197], v[186:189], v[6:9]
	v_mfma_f32_16x16x32_bf16 v[2:5], v[202:205], v[186:189], v[2:5]
	s_setprio 0
	s_add_i32 s41, 0, 0x18000
	v_add_u32_e32 v154, s41, v139
	s_barrier
	ds_read_b128 v[142:145], v154
	ds_read_b128 v[146:149], v154 offset:1024
	ds_read_b128 v[150:153], v154 offset:2048
	ds_read_b128 v[154:157], v154 offset:3072
	s_add_u32 s16, s22, 0x200000
	s_addc_u32 s17, s23, 0
	s_mov_b32 m0, s29
	v_lshl_add_u64 v[190:191], s[16:17], 0, v[0:1]
	ds_read_b128 v[158:161], v141 offset:32768
	ds_read_b128 v[162:165], v141 offset:33792
	ds_read_b128 v[166:169], v141 offset:34816
	ds_read_b128 v[170:173], v141 offset:35840
	ds_read_b128 v[174:177], v141 offset:36864
	ds_read_b128 v[178:181], v141 offset:37888
	ds_read_b128 v[182:185], v141 offset:38912
	ds_read_b128 v[186:189], v141 offset:39936
	global_load_lds_dwordx4 v[190:191], off
	v_lshl_add_u64 v[190:191], s[16:17], 0, v[130:131]
	s_mov_b32 m0, s30
	s_nop 0
	global_load_lds_dwordx4 v[190:191], off
	s_waitcnt lgkmcnt(8)
	s_barrier
	s_waitcnt lgkmcnt(0)
	s_setprio 1
	s_waitcnt lgkmcnt(0)
	v_mfma_f32_16x16x32_bf16 v[126:129], v[142:145], v[158:161], v[126:129]
	v_mfma_f32_16x16x32_bf16 v[122:125], v[150:153], v[158:161], v[122:125]
	v_mfma_f32_16x16x32_bf16 v[110:113], v[142:145], v[166:169], v[110:113]
	v_mfma_f32_16x16x32_bf16 v[106:109], v[150:153], v[166:169], v[106:109]
	v_mfma_f32_16x16x32_bf16 v[94:97], v[142:145], v[174:177], v[94:97]
	v_mfma_f32_16x16x32_bf16 v[90:93], v[150:153], v[174:177], v[90:93]
	v_mfma_f32_16x16x32_bf16 v[78:81], v[142:145], v[182:185], v[78:81]
	v_mfma_f32_16x16x32_bf16 v[74:77], v[150:153], v[182:185], v[74:77]
	v_mfma_f32_16x16x32_bf16 v[126:129], v[146:149], v[162:165], v[126:129]
	v_mfma_f32_16x16x32_bf16 v[122:125], v[154:157], v[162:165], v[122:125]
	v_mfma_f32_16x16x32_bf16 v[110:113], v[146:149], v[170:173], v[110:113]
	v_mfma_f32_16x16x32_bf16 v[106:109], v[154:157], v[170:173], v[106:109]
	v_mfma_f32_16x16x32_bf16 v[94:97], v[146:149], v[178:181], v[94:97]
	v_mfma_f32_16x16x32_bf16 v[90:93], v[154:157], v[178:181], v[90:93]
	v_mfma_f32_16x16x32_bf16 v[78:81], v[146:149], v[186:189], v[78:81]
	v_mfma_f32_16x16x32_bf16 v[74:77], v[154:157], v[186:189], v[74:77]
	s_setprio 0
	s_barrier
	s_add_i32 s22, 0, 0x1c000
	s_add_i32 s16, s41, s28
	v_add_u32_e32 v202, s22, v139
	v_lshl_add_u64 v[136:137], v[136:137], 0, s[44:45]
	s_mov_b32 m0, s16
	ds_read_b128 v[190:193], v202
	ds_read_b128 v[194:197], v202 offset:1024
	ds_read_b128 v[198:201], v202 offset:2048
	ds_read_b128 v[202:205], v202 offset:3072
	global_load_lds_dwordx4 v[136:137], off
	v_lshl_add_u64 v[136:137], v[206:207], 0, s[44:45]
	s_add_i32 m0, s16, 0x2000
	s_nop 0
	global_load_lds_dwordx4 v[136:137], off
	s_barrier
	s_waitcnt lgkmcnt(0)
	s_setprio 1
	s_waitcnt lgkmcnt(0)
	v_mfma_f32_16x16x32_bf16 v[118:121], v[190:193], v[158:161], v[118:121]
	v_mfma_f32_16x16x32_bf16 v[114:117], v[198:201], v[158:161], v[114:117]
	v_mfma_f32_16x16x32_bf16 v[102:105], v[190:193], v[166:169], v[102:105]
	v_mfma_f32_16x16x32_bf16 v[98:101], v[198:201], v[166:169], v[98:101]
	v_mfma_f32_16x16x32_bf16 v[86:89], v[190:193], v[174:177], v[86:89]
	v_mfma_f32_16x16x32_bf16 v[82:85], v[198:201], v[174:177], v[82:85]
	v_mfma_f32_16x16x32_bf16 v[70:73], v[190:193], v[182:185], v[70:73]
	v_mfma_f32_16x16x32_bf16 v[66:69], v[198:201], v[182:185], v[66:69]
	v_mfma_f32_16x16x32_bf16 v[118:121], v[194:197], v[162:165], v[118:121]
	v_mfma_f32_16x16x32_bf16 v[114:117], v[202:205], v[162:165], v[114:117]
	v_mfma_f32_16x16x32_bf16 v[102:105], v[194:197], v[170:173], v[102:105]
	v_mfma_f32_16x16x32_bf16 v[98:101], v[202:205], v[170:173], v[98:101]
	v_mfma_f32_16x16x32_bf16 v[86:89], v[194:197], v[178:181], v[86:89]
	v_mfma_f32_16x16x32_bf16 v[82:85], v[202:205], v[178:181], v[82:85]
	v_mfma_f32_16x16x32_bf16 v[70:73], v[194:197], v[186:189], v[70:73]
	v_mfma_f32_16x16x32_bf16 v[66:69], v[202:205], v[186:189], v[66:69]
	s_setprio 0
	s_mov_b32 m0, s34
	v_lshl_add_u64 v[136:137], v[208:209], 0, s[44:45]
	s_barrier
; #define PG8_STAGE(bufoff, gbase, voff) do { _Pragma("unroll") for (int _i = 0; _i < 2; ++_i) \
;         __builtin_amdgcn_global_load_lds((const unsigned*)((const char*)(gbase) + (voff)[_i]), (LAS unsigned*)(lds + (bufoff) + ldsw + _i * 8192), 16, 0, 0); } while (0)
; #define PG8_LDA(dst, b, h) do { _Pragma("unroll") for (int m = 0; m < 4; ++m) _Pragma("unroll") for (int k = 0; k < 2; ++k) dst[m][k] = *(const LAS bf16x8*)(lds + PG8_SA(b, h) + aoff + m * 2048 + k * 1024); } while (0)
; #define PG8_MMA(ai, bj, At, Bt) do { __builtin_amdgcn_s_setprio(1); _Pragma("unroll") for (int m = 0; m < 4; ++m) _Pragma("unroll") for (int n = 0; n < 2; ++n) _Pragma("unroll") for (int k = 0; k < 2; ++k) \
;         acc[ai][bj][m][n] = __builtin_amdgcn_mfma_f32_16x16x32_bf16(Bt[n][k], At[m][k], acc[ai][bj][m][n], 0, 0, 0); __builtin_amdgcn_s_setprio(0); } while (0)
; #define PG8_WAIT_V(n) asm volatile("s_waitcnt vmcnt(" #n ")" ::: "memory")
; #define PG8_WAIT_L(n) asm volatile("s_waitcnt lgkmcnt(" #n ")" ::: "memory")
; #define PG8_BAR __builtin_amdgcn_s_barrier()
; #define PG8_SCHED __builtin_amdgcn_sched_barrier(0)
; template <class Epi, class Sched>
; __device__ __forceinline__ void gemm_phase(LAS unsigned char* lds, const Gemm g, const Sched& S, const Epi& E) {
;     ...
;             PG8_BAR; PG8_WAIT_L(0); PG8_MMA(0, 1, At, B1); PG8_BAR;
;             PG8_LDA(At, 1, 1); PG8_STAGE(PG8_SA(1, 0), a3, voffA);
;             PG8_BAR; PG8_WAIT_L(0); PG8_MMA(1, 0, At, B0); PG8_BAR; PG8_SCHED;
;             PG8_STAGE(PG8_SB(1, 1), b3 + hstep, voffB);
;             PG8_WAIT_V(6); PG8_BAR; PG8_MMA(1, 1, At, B1); PG8_BAR;
;     __device__ __forceinline__ void operator()(const f32x4 (&acc)[2][2][4][2], const pg8::Unit& u, int wr, int wc, int fr, int fq) const {
;         const int row0 = u.pm * 256 + wr * 64 + fr; const int col0 = u.pn * 256 + wc * 32 + 4 * fq;
; #pragma unroll
;         for (int ai = 0; ai < 2; ++ai)
; #pragma unroll
;             for (int m = 0; m < 4; ++m) { const int row = row0 + ai * 128 + m * 16;
;                 const float* ip; float* op; int b;
;                 if (row < ML_ROWS) { b = row >> 11; ip = xi + (size_t)row * D; op = xo + (size_t)row * D; }
;                 else { b = 8; ip = ci + (size_t)(row - ML_ROWS) * D; op = co + (size_t)(row - ML_ROWS) * D; }
;                 const float* gp = mod + (size_t)b * 12288 + slot * 2048;
	ds_read_b128 v[158:161], v141 offset:49152
	ds_read_b128 v[162:165], v141 offset:50176
	ds_read_b128 v[166:169], v141 offset:51200
	ds_read_b128 v[170:173], v141 offset:52224
	ds_read_b128 v[174:177], v141 offset:53248
	ds_read_b128 v[178:181], v141 offset:54272
	ds_read_b128 v[182:185], v141 offset:55296
	ds_read_b128 v[186:189], v141 offset:56320
	global_load_lds_dwordx4 v[136:137], off
	v_lshl_add_u64 v[136:137], v[210:211], 0, s[44:45]
	s_mov_b32 m0, s35
	s_nop 0
	global_load_lds_dwordx4 v[136:137], off
	s_barrier
	s_waitcnt lgkmcnt(0)
	s_setprio 1
	s_waitcnt lgkmcnt(0)
	v_mfma_f32_16x16x32_bf16 v[62:65], v[142:145], v[158:161], v[62:65]
	v_mfma_f32_16x16x32_bf16 v[58:61], v[150:153], v[158:161], v[58:61]
	v_mfma_f32_16x16x32_bf16 v[46:49], v[142:145], v[166:169], v[46:49]
	v_mfma_f32_16x16x32_bf16 v[42:45], v[150:153], v[166:169], v[42:45]
	v_mfma_f32_16x16x32_bf16 v[30:33], v[142:145], v[174:177], v[30:33]
	v_mfma_f32_16x16x32_bf16 v[26:29], v[150:153], v[174:177], v[26:29]
	v_mfma_f32_16x16x32_bf16 v[14:17], v[142:145], v[182:185], v[14:17]
	v_mfma_f32_16x16x32_bf16 v[10:13], v[150:153], v[182:185], v[10:13]
	v_mfma_f32_16x16x32_bf16 v[62:65], v[146:149], v[162:165], v[62:65]
	v_mfma_f32_16x16x32_bf16 v[58:61], v[154:157], v[162:165], v[58:61]
	v_mfma_f32_16x16x32_bf16 v[46:49], v[146:149], v[170:173], v[46:49]
	v_mfma_f32_16x16x32_bf16 v[42:45], v[154:157], v[170:173], v[42:45]
	v_mfma_f32_16x16x32_bf16 v[30:33], v[146:149], v[178:181], v[30:33]
	v_mfma_f32_16x16x32_bf16 v[26:29], v[154:157], v[178:181], v[26:29]
	v_mfma_f32_16x16x32_bf16 v[14:17], v[146:149], v[186:189], v[14:17]
	v_mfma_f32_16x16x32_bf16 v[10:13], v[154:157], v[186:189], v[10:13]
	s_setprio 0
	s_barrier
	s_add_u32 s16, s20, 0x200080
	s_addc_u32 s17, s21, 0
	s_add_i32 s20, s22, s28
	v_lshl_add_u64 v[136:137], s[16:17], 0, v[0:1]
	s_mov_b32 m0, s20
	s_nop 0
	global_load_lds_dwordx4 v[136:137], off
	v_lshl_add_u64 v[136:137], s[16:17], 0, v[130:131]
	s_add_i32 m0, s20, 0x2000
	s_nop 0
	global_load_lds_dwordx4 v[136:137], off
	s_waitcnt vmcnt(6)
	s_barrier
	s_setprio 1
	v_mfma_f32_16x16x32_bf16 v[54:57], v[190:193], v[158:161], v[54:57]
	v_mfma_f32_16x16x32_bf16 v[50:53], v[198:201], v[158:161], v[50:53]
	v_mfma_f32_16x16x32_bf16 v[38:41], v[190:193], v[166:169], v[38:41]
	v_mfma_f32_16x16x32_bf16 v[34:37], v[198:201], v[166:169], v[34:37]
	v_mfma_f32_16x16x32_bf16 v[22:25], v[190:193], v[174:177], v[22:25]
	v_mfma_f32_16x16x32_bf16 v[18:21], v[198:201], v[174:177], v[18:21]
	v_mfma_f32_16x16x32_bf16 v[6:9], v[190:193], v[182:185], v[6:9]
	v_mfma_f32_16x16x32_bf16 v[2:5], v[198:201], v[182:185], v[2:5]
	v_mfma_f32_16x16x32_bf16 v[54:57], v[194:197], v[162:165], v[54:57]
	v_mfma_f32_16x16x32_bf16 v[50:53], v[202:205], v[162:165], v[50:53]
	v_mfma_f32_16x16x32_bf16 v[38:41], v[194:197], v[170:173], v[38:41]
	v_mfma_f32_16x16x32_bf16 v[34:37], v[202:205], v[170:173], v[34:37]
	v_mfma_f32_16x16x32_bf16 v[22:25], v[194:197], v[178:181], v[22:25]
	v_mfma_f32_16x16x32_bf16 v[18:21], v[202:205], v[178:181], v[18:21]
	v_mfma_f32_16x16x32_bf16 v[6:9], v[194:197], v[186:189], v[6:9]
	v_mfma_f32_16x16x32_bf16 v[2:5], v[202:205], v[186:189], v[2:5]
	s_setprio 0
	s_add_i32 s40, s40, 2
	s_add_u32 s38, s38, 0x100
	s_addc_u32 s39, s39, 0
	s_cmpk_gt_u32 s40, 0x7d
	s_mov_b64 s[16:17], s[18:19]
	s_barrier
	s_cbranch_scc0 .LBB0_1343
	s_lshl_b32 s3, s14, 8
	s_add_i32 s3, s3, s31
	v_readlane_b32 s40, v251, 0
	v_readlane_b32 s41, v251, 1
	v_readlane_b32 s42, v251, 2
	v_readlane_b32 s43, v251, 3
	v_readlane_b32 s44, v251, 4
	v_readlane_b32 s45, v251, 5
	v_readlane_b32 s46, v251, 6
	v_readlane_b32 s47, v251, 7
	v_readlane_b32 s18, v254, 2
	v_readlane_b32 s19, v254, 3
	s_add_i32 s5, s3, 0xffffc000
	s_ashr_i32 s7, s3, 11
	s_cmpk_lt_i32 s3, 0x4000
	s_cselect_b32 s20, s42, s60
	s_cselect_b32 s21, s43, s61
	s_cselect_b32 s5, s3, s5
	s_cselect_b32 s7, s7, 8
	s_mul_i32 s7, s7, 0xc000
	s_add_u32 s18, s18, s7
	s_addc_u32 s19, s19, 0
	s_add_u32 s18, s18, 0xa000
	s_addc_u32 s19, s19, 0
	v_add_u32_e32 v136, s5, v138
	v_lshl_or_b32 v137, s12, 8, v140
	v_lshlrev_b32_e32 v137, 2, v137
	v_lshl_or_b32 v136, v136, 13, v137
	s_mov_b32 s12, s4
	s_mov_b32 s14, s6
	s_mov_b32 s23, 0
	s_cmp_lg_u32 s36, 3
	s_cbranch_scc1 .Lsk_normal
	v_readlane_b32 s5, v253, 24
	s_cmpk_lg_u32 s46, 0x100
	s_cbranch_scc1 .Lsk_normal
	s_cmpk_lg_u32 s5, 0x240
	s_cbranch_scc1 .Lsk_normal
	s_mov_b32 s23, 1
	s_and_b32 s7, s54, 3
	s_lshr_b32 s5, s54, 2
	s_lshl_b32 s5, s5, 5
	v_readlane_b32 s38, v251, 10
	v_readlane_b32 s39, v251, 11
	s_add_u32 s38, s38, s5
	s_addc_u32 s39, s39, 0
	s_add_u32 s38, s38, 0x3700
	s_addc_u32 s39, s39, 0
	s_cmpk_gt_u32 s24, 0x3f
	s_cbranch_scc1 .Lsk_wait_done
	v_mov_b32_e32 v143, 0
	s_mov_b32 s3, 0
.Lsk_spin:
	global_load_dword v144, v143, s[38:39] sc1
	s_waitcnt vmcnt(0)
	v_readfirstlane_b32 s5, v144
	s_cmp_ge_u32 s5, s7
	s_cbranch_scc1 .Lsk_spun
	s_add_i32 s3, s3, 1
	s_cmp_gt_u32 s3, 0x8000
	s_cbranch_scc1 .Lsk_spun
	s_sleep 1
	s_branch .Lsk_spin
.Lsk_spun:
	buffer_inv sc1
	s_waitcnt vmcnt(0)

;     __device__ __forceinline__ void operator()(const f32x4 (&acc)[2][2][4][2], const pg8::Unit& u, int wr, int wc, int fr, int fq) const {
;     ...
;             for (int m = 0; m < 4; ++m) { const int row = row0 + ai * 128 + m * 16;
;                 const float* ip; float* op; int b;
;                 if (row < ML_ROWS) { b = row >> 11; ip = xi + (size_t)row * D; op = xo + (size_t)row * D; }
;                 else { b = 8; ip = ci + (size_t)(row - ML_ROWS) * D; op = co + (size_t)(row - ML_ROWS) * D; }
;                 const float* gp = mod + (size_t)b * 12288 + slot * 2048;
; #pragma unroll
;                 for (int bj = 0; bj < 2; ++bj)
; #pragma unroll
;                     for (int n = 0; n < 2; ++n) { const int c = col0 + bj * 128 + n * 16;
;                         const f32x4 r = *(const f32x4*)(ip + c), g = *(const f32x4*)(gp + c);
;                         *(f32x4*)(op + c) = r + g * acc[ai][bj][m][n]; } }
.Lsk_normal:
	v_add_u32_e32 v142, 0x20000, v136
	v_add_u32_e32 v143, 0x40000, v136
	v_add_u32_e32 v144, 0x60000, v136
	v_add_u32_e32 v145, 0x100000, v136
	v_add_u32_e32 v210, 0x120000, v136
	v_add_u32_e32 v211, 0x140000, v136
	global_load_dwordx4 v[146:149], v137, s[18:19]
	global_load_dwordx4 v[150:153], v137, s[18:19] offset:64
	global_load_dwordx4 v[154:157], v137, s[18:19] offset:512
	global_load_dwordx4 v[158:161], v137, s[18:19] offset:576
	v_add_u32_e32 v137, 0x160000, v136
	global_load_dwordx4 v[162:165], v136, s[20:21]
	global_load_dwordx4 v[166:169], v136, s[20:21] offset:64
	global_load_dwordx4 v[170:173], v136, s[20:21] offset:512
	global_load_dwordx4 v[174:177], v136, s[20:21] offset:576
	global_load_dwordx4 v[178:181], v142, s[20:21]
	global_load_dwordx4 v[182:185], v142, s[20:21] offset:64
	global_load_dwordx4 v[186:189], v142, s[20:21] offset:512
	global_load_dwordx4 v[190:193], v142, s[20:21] offset:576
	global_load_dwordx4 v[194:197], v143, s[20:21]
	global_load_dwordx4 v[198:201], v143, s[20:21] offset:64
	global_load_dwordx4 v[202:205], v143, s[20:21] offset:512
	global_load_dwordx4 v[206:209], v143, s[20:21] offset:576
	s_waitcnt vmcnt(8)
	v_pk_fma_f32 v[126:127], v[126:127], v[146:147], v[162:163]
	v_pk_fma_f32 v[128:129], v[128:129], v[148:149], v[164:165]
	v_pk_fma_f32 v[122:123], v[122:123], v[150:151], v[166:167]
	v_pk_fma_f32 v[124:125], v[124:125], v[152:153], v[168:169]
	v_pk_fma_f32 v[118:119], v[118:119], v[154:155], v[170:171]
	v_pk_fma_f32 v[120:121], v[120:121], v[156:157], v[172:173]
	v_pk_fma_f32 v[114:115], v[114:115], v[158:159], v[174:175]
	v_pk_fma_f32 v[116:117], v[116:117], v[160:161], v[176:177]
	global_store_dwordx4 v136, v[126:129], s[20:21]
	global_store_dwordx4 v136, v[122:125], s[20:21] offset:64
	global_store_dwordx4 v136, v[118:121], s[20:21] offset:512
	global_store_dwordx4 v136, v[114:117], s[20:21] offset:576
	global_load_dwordx4 v[162:165], v144, s[20:21]
	global_load_dwordx4 v[166:169], v144, s[20:21] offset:64
	global_load_dwordx4 v[170:173], v144, s[20:21] offset:512
	global_load_dwordx4 v[174:177], v144, s[20:21] offset:576
	s_waitcnt vmcnt(12)
	v_pk_fma_f32 v[110:111], v[110:111], v[146:147], v[178:179]
	v_pk_fma_f32 v[112:113], v[112:113], v[148:149], v[180:181]
	v_pk_fma_f32 v[106:107], v[106:107], v[150:151], v[182:183]
	v_pk_fma_f32 v[108:109], v[108:109], v[152:153], v[184:185]
	v_pk_fma_f32 v[102:103], v[102:103], v[154:155], v[186:187]
	v_pk_fma_f32 v[104:105], v[104:105], v[156:157], v[188:189]
	v_pk_fma_f32 v[98:99], v[98:99], v[158:159], v[190:191]
	v_pk_fma_f32 v[100:101], v[100:101], v[160:161], v[192:193]
	global_store_dwordx4 v142, v[110:113], s[20:21]
	global_store_dwordx4 v142, v[106:109], s[20:21] offset:64
	global_store_dwordx4 v142, v[102:105], s[20:21] offset:512
	global_store_dwordx4 v142, v[98:101], s[20:21] offset:576
	global_load_dwordx4 v[178:181], v145, s[20:21]
	global_load_dwordx4 v[182:185], v145, s[20:21] offset:64
	global_load_dwordx4 v[186:189], v145, s[20:21] offset:512
	global_load_dwordx4 v[190:193], v145, s[20:21] offset:576
	s_waitcnt vmcnt(16)
	v_pk_fma_f32 v[94:95], v[94:95], v[146:147], v[194:195]
	v_pk_fma_f32 v[96:97], v[96:97], v[148:149], v[196:197]
	v_pk_fma_f32 v[90:91], v[90:91], v[150:151], v[198:199]
	v_pk_fma_f32 v[92:93], v[92:93], v[152:153], v[200:201]
	v_pk_fma_f32 v[86:87], v[86:87], v[154:155], v[202:203]
	v_pk_fma_f32 v[88:89], v[88:89], v[156:157], v[204:205]
	v_pk_fma_f32 v[82:83], v[82:83], v[158:159], v[206:207]
	v_pk_fma_f32 v[84:85], v[84:85], v[160:161], v[208:209]
	global_store_dwordx4 v143, v[94:97], s[20:21]
	global_store_dwordx4 v143, v[90:93], s[20:21] offset:64
	global_store_dwordx4 v143, v[86:89], s[20:21] offset:512
	global_store_dwordx4 v143, v[82:85], s[20:21] offset:576
	global_load_dwordx4 v[194:197], v210, s[20:21]
	global_load_dwordx4 v[198:201], v210, s[20:21] offset:64
	global_load_dwordx4 v[202:205], v210, s[20:21] offset:512
	global_load_dwordx4 v[206:209], v210, s[20:21] offset:576
	s_waitcnt vmcnt(16)
	v_pk_fma_f32 v[78:79], v[78:79], v[146:147], v[162:163]
	v_pk_fma_f32 v[80:81], v[80:81], v[148:149], v[164:165]
	v_pk_fma_f32 v[74:75], v[74:75], v[150:151], v[166:167]
	v_pk_fma_f32 v[76:77], v[76:77], v[152:153], v[168:169]
	v_pk_fma_f32 v[70:71], v[70:71], v[154:155], v[170:171]
	v_pk_fma_f32 v[72:73], v[72:73], v[156:157], v[172:173]
	v_pk_fma_f32 v[66:67], v[66:67], v[158:159], v[174:175]
	v_pk_fma_f32 v[68:69], v[68:69], v[160:161], v[176:177]
	global_store_dwordx4 v144, v[78:81], s[20:21]
	global_store_dwordx4 v144, v[74:77], s[20:21] offset:64
	global_store_dwordx4 v144, v[70:73], s[20:21] offset:512
	global_store_dwordx4 v144, v[66:69], s[20:21] offset:576
	global_load_dwordx4 v[162:165], v211, s[20:21]
	global_load_dwordx4 v[166:169], v211, s[20:21] offset:64
	global_load_dwordx4 v[170:173], v211, s[20:21] offset:512
	global_load_dwordx4 v[174:177], v211, s[20:21] offset:576
	s_waitcnt vmcnt(16)
; #define PG8_WAIT_V(n) asm volatile("s_waitcnt vmcnt(" #n ")" ::: "memory")
; #define PG8_BAR __builtin_amdgcn_s_barrier()
; template <class Epi, class Sched>
; __device__ __forceinline__ void gemm_phase(LAS unsigned char* lds, const Gemm g, const Sched& S, const Epi& E) {
;     ...
;     PG8_WAIT_V(0);
;     if (wr == 0) PG8_BAR;
;     PG8_BAR;
;     __device__ __forceinline__ void operator()(const f32x4 (&acc)[2][2][4][2], const pg8::Unit& u, int wr, int wc, int fr, int fq) const {
;     ...
;                     for (int n = 0; n < 2; ++n) { const int c = col0 + bj * 128 + n * 16;
;                         const f32x4 r = *(const f32x4*)(ip + c), g = *(const f32x4*)(gp + c);
;                         *(f32x4*)(op + c) = r + g * acc[ai][bj][m][n]; } }
	v_pk_fma_f32 v[62:63], v[62:63], v[146:147], v[178:179]
	v_pk_fma_f32 v[64:65], v[64:65], v[148:149], v[180:181]
	v_pk_fma_f32 v[58:59], v[58:59], v[150:151], v[182:183]
	v_pk_fma_f32 v[60:61], v[60:61], v[152:153], v[184:185]
	v_pk_fma_f32 v[54:55], v[54:55], v[154:155], v[186:187]
	v_pk_fma_f32 v[56:57], v[56:57], v[156:157], v[188:189]
	v_pk_fma_f32 v[50:51], v[50:51], v[158:159], v[190:191]
	v_pk_fma_f32 v[52:53], v[52:53], v[160:161], v[192:193]
	global_store_dwordx4 v145, v[62:65], s[20:21]
	global_store_dwordx4 v145, v[58:61], s[20:21] offset:64
	global_store_dwordx4 v145, v[54:57], s[20:21] offset:512
	global_store_dwordx4 v145, v[50:53], s[20:21] offset:576
	global_load_dwordx4 v[178:181], v137, s[20:21]
	global_load_dwordx4 v[182:185], v137, s[20:21] offset:64
	global_load_dwordx4 v[186:189], v137, s[20:21] offset:512
	global_load_dwordx4 v[190:193], v137, s[20:21] offset:576
	s_waitcnt vmcnt(16)
	v_pk_fma_f32 v[46:47], v[46:47], v[146:147], v[194:195]
	v_pk_fma_f32 v[48:49], v[48:49], v[148:149], v[196:197]
	v_pk_fma_f32 v[42:43], v[42:43], v[150:151], v[198:199]
	v_pk_fma_f32 v[44:45], v[44:45], v[152:153], v[200:201]
	v_pk_fma_f32 v[38:39], v[38:39], v[154:155], v[202:203]
	v_pk_fma_f32 v[40:41], v[40:41], v[156:157], v[204:205]
	v_pk_fma_f32 v[34:35], v[34:35], v[158:159], v[206:207]
	v_pk_fma_f32 v[36:37], v[36:37], v[160:161], v[208:209]
	global_store_dwordx4 v210, v[46:49], s[20:21]
	global_store_dwordx4 v210, v[42:45], s[20:21] offset:64
	global_store_dwordx4 v210, v[38:41], s[20:21] offset:512
	global_store_dwordx4 v210, v[34:37], s[20:21] offset:576
	s_waitcnt vmcnt(12)
	v_pk_fma_f32 v[30:31], v[30:31], v[146:147], v[162:163]
	v_pk_fma_f32 v[32:33], v[32:33], v[148:149], v[164:165]
	v_pk_fma_f32 v[26:27], v[26:27], v[150:151], v[166:167]
	v_pk_fma_f32 v[28:29], v[28:29], v[152:153], v[168:169]
	v_pk_fma_f32 v[22:23], v[22:23], v[154:155], v[170:171]
	v_pk_fma_f32 v[24:25], v[24:25], v[156:157], v[172:173]
	v_pk_fma_f32 v[18:19], v[18:19], v[158:159], v[174:175]
	v_pk_fma_f32 v[20:21], v[20:21], v[160:161], v[176:177]
	global_store_dwordx4 v211, v[30:33], s[20:21]
	global_store_dwordx4 v211, v[26:29], s[20:21] offset:64
	global_store_dwordx4 v211, v[22:25], s[20:21] offset:512
	global_store_dwordx4 v211, v[18:21], s[20:21] offset:576
	s_waitcnt vmcnt(8)
	v_pk_fma_f32 v[14:15], v[14:15], v[146:147], v[178:179]
	v_pk_fma_f32 v[16:17], v[16:17], v[148:149], v[180:181]
	v_pk_fma_f32 v[10:11], v[10:11], v[150:151], v[182:183]
	v_pk_fma_f32 v[12:13], v[12:13], v[152:153], v[184:185]
	v_pk_fma_f32 v[6:7], v[6:7], v[154:155], v[186:187]
	v_pk_fma_f32 v[8:9], v[8:9], v[156:157], v[188:189]
	v_pk_fma_f32 v[2:3], v[2:3], v[158:159], v[190:191]
	v_pk_fma_f32 v[4:5], v[4:5], v[160:161], v[192:193]
	global_store_dwordx4 v137, v[14:17], s[20:21]
	global_store_dwordx4 v137, v[10:13], s[20:21] offset:64
	global_store_dwordx4 v137, v[6:9], s[20:21] offset:512
	global_store_dwordx4 v137, v[2:5], s[20:21] offset:576
	s_mov_b64 s[18:19], s[10:11]
	s_mov_b64 s[16:17], s[8:9]
	s_and_b64 vcc, exec, s[0:1]
	s_cbranch_vccz .LBB0_1340
	s_waitcnt vmcnt(0)
	s_cmpk_gt_u32 s24, 0xff
	s_cbranch_scc1 .LBB0_1347
	s_barrier
.LBB0_1347:
	v_mov_b32_e32 v170, v219
	s_barrier
	s_cmp_eq_u32 s23, 0
	s_cbranch_scc1 .Lsk_nosig
	s_cmpk_gt_u32 s24, 0x3f
	s_cbranch_scc1 .Lsk_nosig
	buffer_wbl2 sc1
	s_waitcnt vmcnt(0)
	s_mov_b64 s[20:21], exec
	s_mov_b64 exec, 1
	v_mov_b32_e32 v143, 0
	v_mov_b32_e32 v144, 1
	global_atomic_add v143, v144, s[38:39]
	s_mov_b64 exec, s[20:21]
.Lsk_nosig:
.LBB0_1348:
	s_waitcnt vmcnt(0)
	s_waitcnt lgkmcnt(0)
	s_barrier
	s_mov_b64 s[0:1], exec
	v_readlane_b32 s4, v251, 8
	v_readlane_b32 s5, v251, 9
	s_and_b64 s[4:5], s[0:1], s[4:5]
	s_mov_b64 exec, s[4:5]
	s_cbranch_execz .LBB0_245
	v_readlane_b32 s4, v253, 7
	s_getreg_b32 s3, hwreg(HW_REG_XCC_ID, 0, 4)
	s_waitcnt vmcnt(0) expcnt(0) lgkmcnt(0)
	v_mov_b32_e32 v0, s4
	ds_read_b32 v3, v0
	v_readlane_b32 s4, v253, 8
	s_and_b32 s3, s3, 15
	s_waitcnt lgkmcnt(0)
	v_cmp_ne_u32_e32 vcc, 0, v3
	v_mov_b32_e32 v0, s4
	ds_read_b32 v2, v0
	s_cbranch_vccnz .LBB0_1364
	s_mov_b32 s10, 1
	s_branch .LBB0_1352
